# P9 bias table: its 15 loads are issued into spare VGPRs on entry to grid barrier SEAM(8) (latency hidden by the barrier), P9 only writes them to LDS
# baseline (speedup 1.0000x reference)
; #define LAS __attribute__((address_space(3)))
; __device__ __forceinline__ unsigned xb_add(unsigned* p, unsigned v) { return __hip_atomic_fetch_add(p, v, __ATOMIC_RELAXED, __HIP_MEMORY_SCOPE_AGENT); }
; __device__ __forceinline__ unsigned xb_xcc_id() { return (unsigned)__builtin_amdgcn_s_getreg((3 << 11) | 20) & 0xFu; }
; __device__ __forceinline__ XcdBarrier xcd_barrier_post(unsigned* bar, volatile LAS unsigned* st) {
;     XcdBarrier b; b.bar = bar; b.x = xb_xcc_id(); b.st = st;
;     if (threadIdx.x == 0) (void)xb_add(&bar[XB_XCNT(b.x)], 1u);
;     return b;
; }
; __global__ void __launch_bounds__(512) fwd_kernel(Args args) {
;     ...
;     Frame F; F.lds = (LAS unsigned char*)lds_raw; F.tid = threadIdx.x; F.lane = F.tid & 63; F.wave = __builtin_amdgcn_readfirstlane(F.tid >> 6); F.G = gridDim.x; F.bid = blockIdx.x;
;     cg::grid_group grid = cg::this_grid();
;     volatile LAS unsigned* BST = (volatile LAS unsigned*)(F.lds + LDS_BYTES - 64);
;     if (F.tid < 2) BST[F.tid] = 0u;
;     __syncthreads();
;     XcdBarrier xbar; xbar.bar = (unsigned*)(args.ws + WS_BAR); xbar.x = 0; xbar.st = BST;
;     ...
;     xbar = xcd_barrier_post((unsigned*)(args.ws + WS_BAR), BST);
_Z10fwd_kernel4Args:
	s_mov_b32 s99, 0
	s_mov_b32 s32, 0
	s_load_dwordx8 s[68:75], s[0:1], 0xe0
	s_load_dwordx8 s[4:11], s[0:1], 0xc0
	s_load_dword s97, s[0:1], 0x100
	v_and_b32_e32 v221, 0x3ff, v0
	v_cmp_gt_u32_e32 vcc, 2, v221
	v_readfirstlane_b32 s33, v221
	s_waitcnt lgkmcnt(0)
	v_writelane_b32 v248, s4, 0
	s_nop 1
	v_writelane_b32 v248, s5, 1
	v_writelane_b32 v248, s6, 2
	v_writelane_b32 v248, s7, 3
	v_writelane_b32 v248, s8, 4
	v_writelane_b32 v248, s9, 5
	v_writelane_b32 v248, s10, 6
	v_writelane_b32 v248, s11, 7
	s_add_u32 s6, s0, 0xf8
	s_addc_u32 s7, s1, 0
	s_and_saveexec_b64 s[4:5], vcc
	v_lshl_add_u32 v1, v221, 2, 0
	v_add_u32_e32 v1, 0x23fc0, v1
	v_mov_b32_e32 v2, 0
	ds_write_b32 v1, v2
	s_or_b64 exec, exec, s[4:5]
	s_waitcnt lgkmcnt(0)
	s_barrier
	s_add_u32 s94, s70, 0x300000
	s_getreg_b32 s3, hwreg(HW_REG_XCC_ID, 0, 4)
	s_addc_u32 s95, s71, 0
	s_and_b32 s96, s3, 15
	v_cmp_eq_u32_e64 s[8:9], 0, v221
	s_mov_b64 s[4:5], exec
	s_nop 0
	v_writelane_b32 v248, s8, 8
	s_nop 1
	v_writelane_b32 v248, s9, 9
	s_and_b64 s[8:9], s[4:5], s[8:9]
	s_mov_b64 exec, s[8:9]
	s_cbranch_execz .LBB0_5
	s_mov_b64 s[8:9], exec
	v_mbcnt_lo_u32_b32 v1, s8, 0
	v_mbcnt_hi_u32_b32 v1, s9, v1
	v_cmp_eq_u32_e32 vcc, 0, v1
	s_and_b64 s[10:11], exec, vcc
	s_mov_b64 exec, s[10:11]
	s_cbranch_execz .LBB0_5
	s_lshl_b32 s3, s96, 8
	s_bcnt1_i32_b64 s8, s[8:9]
	v_mov_b32_e32 v1, s3
	v_mov_b32_e32 v2, s8
	global_atomic_add v1, v2, s[94:95] offset:1024

; __device__ __forceinline__ unsigned xb_ld(unsigned* p)              { return __hip_atomic_load(p, __ATOMIC_RELAXED, __HIP_MEMORY_SCOPE_AGENT); }
; __device__ __forceinline__ unsigned xb_add(unsigned* p, unsigned v) { return __hip_atomic_fetch_add(p, v, __ATOMIC_RELAXED, __HIP_MEMORY_SCOPE_AGENT); }
; __device__ __forceinline__ void xcd_barrier_complete(unsigned* bar, unsigned x, unsigned& nloc, unsigned& nx) {
;     const unsigned G = gridDim.x * gridDim.y * gridDim.z;
;     unsigned sum, cnt, mine, sp = 0u;
;     for (;;) {
;         sum = 0u; cnt = 0u; mine = 0u;
; #pragma unroll
;         for (unsigned j = 0; j < 16; ++j) { const unsigned c = xb_ld(&bar[XB_XCNT(j)]); sum += c; cnt += (c > 0u) ? 1u : 0u; mine = (j == x) ? c : mine; }
; __device__ __forceinline__ void xcd_barrier(const XcdBarrier& b) {
;     asm volatile("s_waitcnt vmcnt(0)" ::: "memory");
;     __syncthreads();
;     if (threadIdx.x == 0) {
;         unsigned* bar = b.bar;
;         __builtin_amdgcn_s_waitcnt(0);
;         unsigned nloc = b.st[0], nx = b.st[1];
;         if (nloc == 0u) { xcd_barrier_complete(bar, b.x, nloc, nx); b.st[0] = nloc; b.st[1] = nx; }
;         const unsigned old = xb_add(&bar[XB_XSUB(b.x)], 1u);
;         const unsigned gen = old / nloc;
;         if (old + 1u == (gen + 1u) * nloc) {
.LBB0_845:
	s_cmp_gt_i32 s73, 9
	s_cselect_b64 s[0:1], -1, 0
	s_and_b64 s[4:5], s[4:5], s[0:1]
	s_andn2_b64 vcc, exec, s[4:5]
	s_cbranch_vccnz .LBB0_899
	v_lshlrev_b32_e32 v120, 2, v221
	v_add_u32_e32 v121, 0x1000, v120
	v_add_u32_e32 v122, 0x2000, v120
	v_add_u32_e32 v123, 0x3000, v120
	v_add_u32_e32 v124, 0x4000, v120
	v_add_u32_e32 v125, 0x5000, v120
	v_add_u32_e32 v126, 0x6000, v120
	v_add_u32_e32 v127, 0x7000, v120
	global_load_dword v100, v120, s[24:25]
	global_load_dword v101, v120, s[24:25] offset:2048
	global_load_dword v102, v121, s[24:25]
	global_load_dword v103, v121, s[24:25] offset:2048
	global_load_dword v104, v122, s[24:25]
	global_load_dword v105, v122, s[24:25] offset:2048
	global_load_dword v106, v123, s[24:25]
	global_load_dword v107, v123, s[24:25] offset:2048
	global_load_dword v108, v124, s[24:25]
	global_load_dword v109, v124, s[24:25] offset:2048
	global_load_dword v110, v125, s[24:25]
	global_load_dword v111, v125, s[24:25] offset:2048
	global_load_dword v112, v126, s[24:25]
	global_load_dword v113, v126, s[24:25] offset:2048
	v_cmp_gt_u32_e32 vcc, 0x110, v221
	s_nop 1
	s_and_saveexec_b64 s[6:7], vcc
	global_load_dword v114, v127, s[24:25]
	s_mov_b64 exec, s[6:7]
	s_mov_b32 s32, 1
	s_waitcnt vmcnt(0)
	s_waitcnt lgkmcnt(0)
	s_barrier
	s_mov_b64 s[4:5], exec
	v_readlane_b32 s6, v248, 8
	v_readlane_b32 s7, v248, 9
	s_and_b64 s[6:7], s[4:5], s[6:7]
	s_mov_b64 exec, s[6:7]
	s_cbranch_execz .LBB0_898
	s_add_i32 s3, 0, 0x23fc0
	v_mov_b32_e32 v0, s3
	s_waitcnt vmcnt(0) expcnt(0) lgkmcnt(0)
	ds_read_b32 v2, v0
	s_add_i32 s3, 0, 0x23fc4
	v_mov_b32_e32 v0, s3
	ds_read_b32 v0, v0
	s_waitcnt lgkmcnt(1)
	v_cmp_ne_u32_e32 vcc, 0, v2
	s_cbranch_vccnz .LBB0_862
	s_add_u32 s6, s70, 0x300200
	s_addc_u32 s7, s71, 0
	s_add_u32 s8, s70, 0x300400
	s_addc_u32 s9, s71, 0
	s_add_u32 s10, s70, 0x300500
	s_addc_u32 s11, s71, 0
	s_add_u32 s12, s70, 0x300600
	s_addc_u32 s13, s71, 0
	s_add_u32 s14, s70, 0x300700
	s_addc_u32 s15, s71, 0
	s_add_u32 s16, s70, 0x300800
	s_addc_u32 s17, s71, 0
	s_add_u32 s18, s70, 0x300900
	s_addc_u32 s19, s71, 0
	s_add_u32 s20, s70, 0x300a00
	s_addc_u32 s21, s71, 0
	s_add_u32 s22, s70, 0x300b00
	s_addc_u32 s23, s71, 0
	s_add_u32 s26, s70, 0x300c00
	s_addc_u32 s27, s71, 0
	s_add_u32 s28, s70, 0x300d00
	s_addc_u32 s29, s71, 0
	s_add_u32 s30, s70, 0x300e00
	s_addc_u32 s31, s71, 0
	s_add_u32 s34, s70, 0x300f00
	s_addc_u32 s35, s71, 0
	s_add_u32 s36, s70, 0x301000
	s_addc_u32 s37, s71, 0
	s_add_u32 s46, s70, 0x301100
	s_addc_u32 s47, s71, 0
	s_add_u32 s48, s70, 0x301200
	s_addc_u32 s49, s71, 0
	s_mul_i32 s3, s97, s74
	s_add_u32 s50, s70, 0x301300
	s_mul_i32 s3, s3, s75
	s_addc_u32 s51, s71, 0
	s_mov_b32 s33, 1
	v_mov_b32_e32 v16, 0
	s_branch .LBB0_850

; #define LAS __attribute__((address_space(3)))
; __device__ __forceinline__ void na_phase(const Frame& F, const bf16* QH, const bf16* VB, const float* rpb, bf16* U) {
;     const bf16* KH = QH + (size_t)16 * MTOK * 64;
;     LAS float* RP = (LAS float*)F.lds;
;     for (int i = F.tid; i < 16 * 465; i += 512) RP[i] = rpb[i];
;     __syncthreads();
;     const int lane = F.lane, n = lane & 15, q4 = lane >> 4;
;     const int vcu = (F.G % 8 == 0) ? (F.bid % 8) * (F.G / 8) + F.bid / 8 : F.bid;
;     for (int br = vcu; br < MB * 256; br += F.G) {
;         const int b = br >> 8, r = br & 255;
;         const int rs = min(max(r - 4, 0), 248);
; #pragma unroll 1
;         for (int it = 0; it < 8; ++it) {
;             const int hj = it * 8 + F.wave, h = hj >> 2, j = hj & 3;
;             const int c0 = (j == 0) ? 0 : (j == 1) ? 8 : (j == 2) ? 24 : 32;
;             const int qcol = 16 * j + n, cs = min(max(qcol - 8, 0), 48);
;             const size_t tokq = (size_t)b * SEQL + r * 64 + qcol;
.LBB0_899:
	s_cmp_lt_i32 s72, 10
	s_cselect_b64 s[4:5], -1, 0
	s_and_b64 s[36:37], s[4:5], s[0:1]
	s_andn2_b64 vcc, exec, s[36:37]
	s_cbranch_vccnz .LBB0_913
	v_lshlrev_b32_e32 v4, 2, v221
	v_add_u32_e32 v3, 0, v4
	s_waitcnt lgkmcnt(0)
	s_cmp_eq_u32 s32, 1
	s_cbranch_scc0 .Lrp_orig
	s_mov_b32 s32, 0
	s_waitcnt vmcnt(0)
	ds_write_b32 v3, v100
	ds_write_b32 v3, v101 offset:2048
	ds_write_b32 v3, v102 offset:4096
	ds_write_b32 v3, v103 offset:6144
	ds_write_b32 v3, v104 offset:8192
	ds_write_b32 v3, v105 offset:10240
	ds_write_b32 v3, v106 offset:12288
	ds_write_b32 v3, v107 offset:14336
	ds_write_b32 v3, v108 offset:16384
	ds_write_b32 v3, v109 offset:18432
	ds_write_b32 v3, v110 offset:20480
	ds_write_b32 v3, v111 offset:22528
	ds_write_b32 v3, v112 offset:24576
	ds_write_b32 v3, v113 offset:26624
	v_cmp_gt_u32_e32 vcc, 0x110, v221
	s_nop 1
	s_and_saveexec_b64 s[0:1], vcc
	ds_write_b32 v3, v114 offset:28672
	s_mov_b64 exec, s[0:1]
	s_branch .Lrp_done
.Lrp_orig:
	v_add_u32_e32 v6, 0x1000, v4
	v_add_u32_e32 v7, 0x2000, v4
	v_add_u32_e32 v8, 0x3000, v4
	v_add_u32_e32 v9, 0x4000, v4
	v_add_u32_e32 v26, 0x5000, v4
	v_add_u32_e32 v27, 0x6000, v4
	v_add_u32_e32 v28, 0x7000, v4
	global_load_dword v10, v4, s[24:25]
	global_load_dword v11, v4, s[24:25] offset:2048
	global_load_dword v12, v6, s[24:25]
	global_load_dword v13, v6, s[24:25] offset:2048
	global_load_dword v14, v7, s[24:25]
	global_load_dword v15, v7, s[24:25] offset:2048
	global_load_dword v16, v8, s[24:25]
	global_load_dword v17, v8, s[24:25] offset:2048
	global_load_dword v18, v9, s[24:25]
	global_load_dword v19, v9, s[24:25] offset:2048
	global_load_dword v20, v26, s[24:25]
	global_load_dword v21, v26, s[24:25] offset:2048
	global_load_dword v22, v27, s[24:25]
	global_load_dword v23, v27, s[24:25] offset:2048
	v_cmp_gt_u32_e32 vcc, 0x110, v221
	s_nop 1
	s_and_saveexec_b64 s[0:1], vcc
	global_load_dword v24, v28, s[24:25]
	s_mov_b64 exec, s[0:1]
	s_waitcnt vmcnt(0)
	ds_write_b32 v3, v10
	ds_write_b32 v3, v11 offset:2048
	ds_write_b32 v3, v12 offset:4096
	ds_write_b32 v3, v13 offset:6144
	ds_write_b32 v3, v14 offset:8192
	ds_write_b32 v3, v15 offset:10240
	ds_write_b32 v3, v16 offset:12288
	ds_write_b32 v3, v17 offset:14336
	ds_write_b32 v3, v18 offset:16384
	ds_write_b32 v3, v19 offset:18432
	ds_write_b32 v3, v20 offset:20480
	ds_write_b32 v3, v21 offset:22528
	ds_write_b32 v3, v22 offset:24576
	ds_write_b32 v3, v23 offset:26624
	s_and_saveexec_b64 s[0:1], vcc
	ds_write_b32 v3, v24 offset:28672
	s_mov_b64 exec, s[0:1]
.Lrp_done:
	s_ashr_i32 s1, s2, 31
	s_lshr_b32 s1, s1, 29
	s_add_i32 s1, s2, s1
	s_ashr_i32 s3, s1, 3
	s_and_b32 s1, s1, -8
	s_sub_i32 s1, s2, s1
	s_ashr_i32 s4, s74, 3
	s_mul_i32 s1, s4, s1
	s_and_b32 s0, s74, 7
	s_add_i32 s1, s1, s3
	s_cmp_eq_u32 s0, 0
	s_cselect_b32 s3, s1, s2
	s_mov_b32 s47, 0
	s_cmpk_lt_i32 s3, 0x200
	s_waitcnt lgkmcnt(0)
	s_barrier
	s_cbranch_scc0 .LBB0_912
	v_mbcnt_lo_u32_b32 v3, -1, 0
	v_readlane_b32 s0, v248, 14
	v_mbcnt_hi_u32_b32 v3, -1, v3
	s_bfe_u32 s6, s0, 0x20006
	v_and_b32_e32 v5, 64, v3
	s_lshl_b32 s8, s6, 4
	v_xor_b32_e32 v4, 16, v3
	v_add_u32_e32 v5, 64, v5
	s_cmp_eq_u32 s6, 2
	v_cmp_lt_i32_e32 vcc, v4, v5
	v_and_b32_e32 v0, 15, v221
	v_lshrrev_b32_e32 v72, 4, v220
	s_cselect_b32 s7, 24, 32
	v_cndmask_b32_e32 v4, v3, v4, vcc
	s_lshr_b32 s46, s0, 8
	v_or_b32_e32 v1, s8, v0
	v_lshlrev_b32_e32 v48, 3, v72
	v_lshlrev_b32_e32 v73, 2, v4
	v_xor_b32_e32 v4, 32, v3
	s_lshl_b64 s[0:1], s[46:47], 22
	v_sub_u32_e64 v1, v1, 8 clamp
	v_cmp_lt_i32_e32 vcc, v4, v5
	v_lshl_or_b32 v52, v0, 4, s0
	v_mov_b32_e32 v53, s1
	v_add_u32_e32 v75, s8, v0
	v_sub_u32_e32 v0, v48, v0
	s_mul_i32 s1, s46, 0x744
	v_min_u32_e32 v49, 48, v1
	v_mov_b32_e32 v51, 0
	v_lshlrev_b32_e32 v1, 1, v221
	v_and_b32_e32 v2, 3, v221
	v_cndmask_b32_e32 v3, v3, v4, vcc
	v_lshl_or_b32 v50, s46, 7, v48
	s_mov_b64 s[4:5], 0x8000040
	v_subrev_u32_e32 v76, s8, v0
	s_add_i32 s33, s1, 0
	v_add_u32_e32 v57, 16, v49
	v_lshlrev_b32_e32 v74, 2, v3
	v_lshl_add_u64 v[54:55], v[50:51], 0, s[4:5]
	s_addk_i32 s33, 0x364
	v_and_or_b32 v56, v1, 24, v2
	s_cmp_eq_u32 s6, 0
	s_cselect_b32 s98, 0, s7
	s_cmp_eq_u32 s6, 1
	s_cselect_b32 s98, 8, s98
	s_lshl_b32 s98, s98, 3
	v_and_b32_e32 v252, 15, v221
	v_lshrrev_b32_e32 v253, 2, v252
	v_and_b32_e32 v254, 3, v252
	v_lshlrev_b32_e32 v249, 10, v72
	v_lshl_or_b32 v250, v254, 4, v249
	v_lshl_or_b32 v249, v253, 6, v250
	v_add_u32_e32 v249, s98, v249
	v_and_b32_e32 v254, 1, v253
	v_lshl_or_b32 v250, v254, 9, v250
	v_lshrrev_b32_e32 v254, 3, v252
	v_lshl_add_u32 v254, s6, 1, v254
	v_lshl_or_b32 v250, v254, 6, v250
	v_mov_b32_e32 v58, s0
	s_mov_b64 s[90:91], -1
	s_mov_b64 s[92:93], -1
	s_mov_b64 s[98:99], 0
	s_cmp_eq_u32 s6, 0
	s_cselect_b32 s90, 0x0fff0fff, s90
	s_cselect_b32 s91, 0x0fff0fff, s91
	s_cselect_b32 s93, 0x0000ffff, s93
	s_cselect_b32 s99, 0xffff0000, s99
	s_cmp_eq_u32 s6, 3
	s_cselect_b32 s90, 0xfff0fff0, s90
	s_cselect_b32 s91, 0xfff0fff0, s91
	s_cselect_b32 s92, 0xffff0000, s92
	s_cselect_b32 s98, 0x0000ffff, s98
	v_mov_b32_e32 v59, v53
	v_add_u32_e32 v77, 1, v76
	v_add_u32_e32 v78, 2, v76
	v_add_u32_e32 v79, 3, v76
	v_add_u32_e32 v80, 4, v76
	v_add_u32_e32 v81, 5, v76
	v_add_u32_e32 v82, 6, v76
	v_add_u32_e32 v83, 7, v76
	s_movk_i32 s52, 0x7c
	s_brev_b32 s53, 8
	s_mov_b32 s54, 0x10200000
	s_mov_b32 s55, 0x10001000
	s_mov_b32 s56, 0x10201000
	s_mov_b32 s57, 0x10002000
	s_mov_b32 s58, 0x10202000
	s_mov_b32 s59, 0x10003000
	s_mov_b32 s60, 0x10203000
	s_mov_b32 s61, 0x10004000
	s_mov_b32 s62, 0x10204000
	s_mov_b32 s63, 0x10005000
	s_mov_b32 s64, 0x10205000
	s_mov_b32 s65, 0x10006000
	s_mov_b32 s66, 0x10206000
	s_mov_b32 s67, 0x10007000
	s_mov_b32 s76, 0x10207000
	s_mov_b32 s77, 0xff61b1e6
	v_mov_b32_e32 v84, 0xff61b1e6
	s_brev_b32 s78, 40
	s_mov_b32 s79, 0x14002000
	s_mov_b32 s80, 0x14004000
	s_mov_b32 s81, 0x14006000
	s_mov_b32 s82, 0x14008000
	s_mov_b32 s83, 0x1400a000
	s_mov_b32 s84, 0x1400c000
	s_mov_b32 s85, 0x1400e000
	s_mov_b64 s[48:49], 0x800000
	s_mov_b64 s[50:51], 0x100
	s_mov_b32 s86, s3
	s_branch .LBB0_905
